# v93 + LDS-DMA offset:128 with M0-128 (72 VALU 64-bit adds removed from GEMM loops) + RESID permlane-swap butterflies
# speedup vs baseline: 1.0068x; 1.0068x over previous
.LBB0_649:
	s_add_i32 s42, s4, 2
	s_add_i32 s43, 0, 0x10000
	s_cmp_eq_u32 s35, s4
	v_lshl_add_u64 v[132:133], v[130:131], 0, s[84:85]
	s_cselect_b64 vcc, -1, 0
	v_add_u32_e32 v144, s43, v237
	v_cndmask_b32_e32 v157, v133, v177, vcc
	v_cndmask_b32_e32 v156, v132, v176, vcc
	ds_read_b128 v[132:135], v144
	ds_read_b128 v[136:139], v144 offset:1024
	ds_read_b128 v[140:143], v144 offset:2048
	ds_read_b128 v[144:147], v144 offset:3072
	s_cselect_b32 s4, s0, s6
	s_cselect_b32 s5, s1, s7
	v_lshl_add_u64 v[202:203], v[130:131], 0, v[172:173]
	s_add_i32 m0, s8, 0xc000
	ds_read_b128 v[148:151], v243
	ds_read_b128 v[152:155], v243 offset:1024
	ds_read_b128 v[178:181], v243 offset:2048
	ds_read_b128 v[182:185], v243 offset:3072
	ds_read_b128 v[186:189], v243 offset:4096
	ds_read_b128 v[190:193], v243 offset:5120
	ds_read_b128 v[194:197], v243 offset:6144
	ds_read_b128 v[198:201], v243 offset:7168
	global_load_lds_dwordx4 v[202:203], off
	v_lshl_add_u64 v[202:203], v[130:131], 0, v[174:175]
	s_add_i32 m0, s8, 0xe000
	s_nop 0
	global_load_lds_dwordx4 v[202:203], off
	s_waitcnt lgkmcnt(8)
	s_barrier
	s_waitcnt lgkmcnt(0)
	s_waitcnt lgkmcnt(0)
	v_mfma_f32_16x16x32_bf16 v[126:129], v[132:135], v[148:151], v[126:129]
	v_mfma_f32_16x16x32_bf16 v[122:125], v[140:143], v[148:151], v[122:125]
	v_mfma_f32_16x16x32_bf16 v[110:113], v[132:135], v[178:181], v[110:113]
	v_mfma_f32_16x16x32_bf16 v[106:109], v[140:143], v[178:181], v[106:109]
	v_mfma_f32_16x16x32_bf16 v[98:101], v[132:135], v[186:189], v[98:101]
	v_mfma_f32_16x16x32_bf16 v[90:93], v[140:143], v[186:189], v[90:93]
	v_mfma_f32_16x16x32_bf16 v[82:85], v[132:135], v[194:197], v[82:85]
	v_mfma_f32_16x16x32_bf16 v[74:77], v[140:143], v[194:197], v[74:77]
	v_mfma_f32_16x16x32_bf16 v[126:129], v[136:139], v[152:155], v[126:129]
	v_mfma_f32_16x16x32_bf16 v[122:125], v[144:147], v[152:155], v[122:125]
	v_mfma_f32_16x16x32_bf16 v[110:113], v[136:139], v[182:185], v[110:113]
	v_mfma_f32_16x16x32_bf16 v[106:109], v[144:147], v[182:185], v[106:109]
	v_mfma_f32_16x16x32_bf16 v[98:101], v[136:139], v[190:193], v[98:101]
	v_mfma_f32_16x16x32_bf16 v[90:93], v[144:147], v[190:193], v[90:93]
	v_mfma_f32_16x16x32_bf16 v[82:85], v[136:139], v[198:201], v[82:85]
	v_mfma_f32_16x16x32_bf16 v[74:77], v[144:147], v[198:201], v[74:77]
	s_barrier
	s_add_i32 s89, 0, 0x14000
	s_add_i32 s43, s43, s3
	v_add_u32_e32 v169, s89, v237
	v_lshl_add_u64 v[218:219], s[4:5], 0, v[162:163]
	s_mov_b32 m0, s43
	ds_read_b128 v[202:205], v169
	ds_read_b128 v[206:209], v169 offset:1024
	ds_read_b128 v[210:213], v169 offset:2048
	ds_read_b128 v[214:217], v169 offset:3072
	global_load_lds_dwordx4 v[218:219], off
	v_lshl_add_u64 v[224:225], s[4:5], 0, v[166:167]
	s_add_i32 m0, s43, 0x2000
	s_nop 0
	global_load_lds_dwordx4 v[224:225], off
	s_barrier
	s_waitcnt lgkmcnt(0)
	s_waitcnt lgkmcnt(0)
	v_mfma_f32_16x16x32_bf16 v[118:121], v[202:205], v[148:151], v[118:121]
	v_mfma_f32_16x16x32_bf16 v[114:117], v[210:213], v[148:151], v[114:117]
	v_mfma_f32_16x16x32_bf16 v[102:105], v[202:205], v[178:181], v[102:105]
	v_mfma_f32_16x16x32_bf16 v[94:97], v[210:213], v[178:181], v[94:97]
	v_mfma_f32_16x16x32_bf16 v[86:89], v[202:205], v[186:189], v[86:89]
	v_mfma_f32_16x16x32_bf16 v[78:81], v[210:213], v[186:189], v[78:81]
	v_mfma_f32_16x16x32_bf16 v[70:73], v[202:205], v[194:197], v[70:73]
	v_mfma_f32_16x16x32_bf16 v[66:69], v[210:213], v[194:197], v[66:69]
	v_mfma_f32_16x16x32_bf16 v[118:121], v[206:209], v[152:155], v[118:121]
	v_mfma_f32_16x16x32_bf16 v[114:117], v[214:217], v[152:155], v[114:117]
	v_mfma_f32_16x16x32_bf16 v[102:105], v[206:209], v[182:185], v[102:105]
	v_mfma_f32_16x16x32_bf16 v[94:97], v[214:217], v[182:185], v[94:97]
	v_mfma_f32_16x16x32_bf16 v[86:89], v[206:209], v[190:193], v[86:89]
	v_mfma_f32_16x16x32_bf16 v[78:81], v[214:217], v[190:193], v[78:81]
	v_mfma_f32_16x16x32_bf16 v[70:73], v[206:209], v[198:201], v[70:73]
	v_mfma_f32_16x16x32_bf16 v[66:69], v[214:217], v[198:201], v[66:69]
	s_mov_b32 m0, s8
	v_lshl_add_u64 v[230:231], v[156:157], 0, v[160:161]
	s_barrier
	ds_read_b128 v[148:151], v243 offset:16384
	ds_read_b128 v[152:155], v243 offset:17408
	ds_read_b128 v[178:181], v243 offset:18432
	ds_read_b128 v[182:185], v243 offset:19456
	ds_read_b128 v[186:189], v243 offset:20480
	ds_read_b128 v[190:193], v243 offset:21504
	ds_read_b128 v[194:197], v243 offset:22528
	ds_read_b128 v[198:201], v243 offset:23552
	global_load_lds_dwordx4 v[230:231], off
	v_lshl_add_u64 v[232:233], v[156:157], 0, v[164:165]
	s_mov_b32 m0, s9
	s_nop 0
	global_load_lds_dwordx4 v[232:233], off
	s_barrier
	s_waitcnt lgkmcnt(0)
	s_waitcnt lgkmcnt(0)
	v_mfma_f32_16x16x32_bf16 v[62:65], v[132:135], v[148:151], v[62:65]
	v_mfma_f32_16x16x32_bf16 v[58:61], v[140:143], v[148:151], v[58:61]
	v_mfma_f32_16x16x32_bf16 v[46:49], v[132:135], v[178:181], v[46:49]
	v_mfma_f32_16x16x32_bf16 v[42:45], v[140:143], v[178:181], v[42:45]
	v_mfma_f32_16x16x32_bf16 v[34:37], v[132:135], v[186:189], v[34:37]
	v_mfma_f32_16x16x32_bf16 v[26:29], v[140:143], v[186:189], v[26:29]
	v_mfma_f32_16x16x32_bf16 v[18:21], v[132:135], v[194:197], v[18:21]
	v_mfma_f32_16x16x32_bf16 v[10:13], v[140:143], v[194:197], v[10:13]
	v_mfma_f32_16x16x32_bf16 v[62:65], v[136:139], v[152:155], v[62:65]
	v_mfma_f32_16x16x32_bf16 v[58:61], v[144:147], v[152:155], v[58:61]
	v_mfma_f32_16x16x32_bf16 v[46:49], v[136:139], v[182:185], v[46:49]
	v_mfma_f32_16x16x32_bf16 v[42:45], v[144:147], v[182:185], v[42:45]
	v_mfma_f32_16x16x32_bf16 v[34:37], v[136:139], v[190:193], v[34:37]
	v_mfma_f32_16x16x32_bf16 v[26:29], v[144:147], v[190:193], v[26:29]
	v_mfma_f32_16x16x32_bf16 v[18:21], v[136:139], v[198:201], v[18:21]
	v_mfma_f32_16x16x32_bf16 v[10:13], v[144:147], v[198:201], v[10:13]
	s_barrier
	s_add_u32 s4, s4, s94
	s_addc_u32 s5, s5, 0
	s_add_i32 s43, s89, s3
	v_lshl_add_u64 v[244:245], s[4:5], 0, v[162:163]
	s_mov_b32 m0, s43
	v_lshl_add_u64 v[246:247], s[4:5], 0, v[166:167]
	global_load_lds_dwordx4 v[244:245], off
	s_add_i32 m0, s43, 0x2000
	s_nop 0
	global_load_lds_dwordx4 v[246:247], off
	s_waitcnt vmcnt(6)
	s_barrier
	v_mfma_f32_16x16x32_bf16 v[54:57], v[202:205], v[148:151], v[54:57]
	v_mfma_f32_16x16x32_bf16 v[50:53], v[210:213], v[148:151], v[50:53]
	v_mfma_f32_16x16x32_bf16 v[38:41], v[202:205], v[178:181], v[38:41]
	v_mfma_f32_16x16x32_bf16 v[30:33], v[210:213], v[178:181], v[30:33]
	v_mfma_f32_16x16x32_bf16 v[22:25], v[202:205], v[186:189], v[22:25]
	v_mfma_f32_16x16x32_bf16 v[14:17], v[210:213], v[186:189], v[14:17]
	v_mfma_f32_16x16x32_bf16 v[6:9], v[202:205], v[194:197], v[6:9]
	v_mfma_f32_16x16x32_bf16 v[2:5], v[210:213], v[194:197], v[2:5]
	v_mfma_f32_16x16x32_bf16 v[54:57], v[206:209], v[152:155], v[54:57]
	v_mfma_f32_16x16x32_bf16 v[50:53], v[214:217], v[152:155], v[50:53]
	v_mfma_f32_16x16x32_bf16 v[38:41], v[206:209], v[182:185], v[38:41]
	v_mfma_f32_16x16x32_bf16 v[30:33], v[214:217], v[182:185], v[30:33]
	v_mfma_f32_16x16x32_bf16 v[22:25], v[206:209], v[190:193], v[22:25]
	v_mfma_f32_16x16x32_bf16 v[14:17], v[214:217], v[190:193], v[14:17]
	v_mfma_f32_16x16x32_bf16 v[6:9], v[206:209], v[198:201], v[6:9]
	v_mfma_f32_16x16x32_bf16 v[2:5], v[214:217], v[198:201], v[2:5]
	s_add_i32 s4, 0, 0x18000
	v_add_u32_e32 v144, s4, v237
	s_barrier
	ds_read_b128 v[132:135], v144
	ds_read_b128 v[136:139], v144 offset:1024
	ds_read_b128 v[140:143], v144 offset:2048
	ds_read_b128 v[144:147], v144 offset:3072
	v_lshl_add_u64 v[156:157], v[156:157], 0, s[94:95]
	s_mov_b32 m0, s10
	v_lshl_add_u64 v[202:203], v[156:157], 0, v[160:161]
	ds_read_b128 v[148:151], v243 offset:32768
	ds_read_b128 v[152:155], v243 offset:33792
	ds_read_b128 v[178:181], v243 offset:34816
	ds_read_b128 v[182:185], v243 offset:35840
	ds_read_b128 v[186:189], v243 offset:36864
	ds_read_b128 v[190:193], v243 offset:37888
	ds_read_b128 v[194:197], v243 offset:38912
	ds_read_b128 v[198:201], v243 offset:39936
	global_load_lds_dwordx4 v[202:203], off
	v_lshl_add_u64 v[156:157], v[156:157], 0, v[164:165]
	s_mov_b32 m0, s11
	s_nop 0
	global_load_lds_dwordx4 v[156:157], off
	s_waitcnt lgkmcnt(8)
	s_barrier
	s_waitcnt lgkmcnt(0)
	s_waitcnt lgkmcnt(0)
	v_mfma_f32_16x16x32_bf16 v[126:129], v[132:135], v[148:151], v[126:129]
	v_mfma_f32_16x16x32_bf16 v[122:125], v[140:143], v[148:151], v[122:125]
	v_mfma_f32_16x16x32_bf16 v[110:113], v[132:135], v[178:181], v[110:113]
	v_mfma_f32_16x16x32_bf16 v[106:109], v[140:143], v[178:181], v[106:109]
	v_mfma_f32_16x16x32_bf16 v[98:101], v[132:135], v[186:189], v[98:101]
	v_mfma_f32_16x16x32_bf16 v[90:93], v[140:143], v[186:189], v[90:93]
	v_mfma_f32_16x16x32_bf16 v[82:85], v[132:135], v[194:197], v[82:85]
	v_mfma_f32_16x16x32_bf16 v[74:77], v[140:143], v[194:197], v[74:77]
	v_mfma_f32_16x16x32_bf16 v[126:129], v[136:139], v[152:155], v[126:129]
	v_mfma_f32_16x16x32_bf16 v[122:125], v[144:147], v[152:155], v[122:125]
	v_mfma_f32_16x16x32_bf16 v[110:113], v[136:139], v[182:185], v[110:113]
	v_mfma_f32_16x16x32_bf16 v[106:109], v[144:147], v[182:185], v[106:109]
	v_mfma_f32_16x16x32_bf16 v[98:101], v[136:139], v[190:193], v[98:101]
	v_mfma_f32_16x16x32_bf16 v[90:93], v[144:147], v[190:193], v[90:93]
	v_mfma_f32_16x16x32_bf16 v[82:85], v[136:139], v[198:201], v[82:85]
	v_mfma_f32_16x16x32_bf16 v[74:77], v[144:147], v[198:201], v[74:77]
	s_barrier
	s_add_i32 s5, 0, 0x1c000
	v_add_u32_e32 v156, s5, v237
	s_add_i32 s4, s4, s3
	ds_read_b128 v[202:205], v156
	ds_read_b128 v[206:209], v156 offset:1024
	ds_read_b128 v[210:213], v156 offset:2048
	ds_read_b128 v[214:217], v156 offset:3072
	s_add_i32 m0, s4, 0xffffff80
	s_nop 0
	global_load_lds_dwordx4 v[218:219], off offset:128
	s_add_i32 m0, s4, 0x1f80
	s_nop 0
	global_load_lds_dwordx4 v[224:225], off offset:128
	s_barrier
	s_waitcnt lgkmcnt(0)
	s_waitcnt lgkmcnt(0)
	v_mfma_f32_16x16x32_bf16 v[118:121], v[202:205], v[148:151], v[118:121]
	v_mfma_f32_16x16x32_bf16 v[114:117], v[210:213], v[148:151], v[114:117]
	v_mfma_f32_16x16x32_bf16 v[102:105], v[202:205], v[178:181], v[102:105]
	v_mfma_f32_16x16x32_bf16 v[94:97], v[210:213], v[178:181], v[94:97]
	v_mfma_f32_16x16x32_bf16 v[86:89], v[202:205], v[186:189], v[86:89]
	v_mfma_f32_16x16x32_bf16 v[78:81], v[210:213], v[186:189], v[78:81]
	v_mfma_f32_16x16x32_bf16 v[70:73], v[202:205], v[194:197], v[70:73]
	v_mfma_f32_16x16x32_bf16 v[66:69], v[210:213], v[194:197], v[66:69]
	v_mfma_f32_16x16x32_bf16 v[118:121], v[206:209], v[152:155], v[118:121]
	v_mfma_f32_16x16x32_bf16 v[114:117], v[214:217], v[152:155], v[114:117]
	v_mfma_f32_16x16x32_bf16 v[102:105], v[206:209], v[182:185], v[102:105]
	v_mfma_f32_16x16x32_bf16 v[94:97], v[214:217], v[182:185], v[94:97]
	v_mfma_f32_16x16x32_bf16 v[86:89], v[206:209], v[190:193], v[86:89]
	v_mfma_f32_16x16x32_bf16 v[78:81], v[214:217], v[190:193], v[78:81]
	v_mfma_f32_16x16x32_bf16 v[70:73], v[206:209], v[198:201], v[70:73]
	v_mfma_f32_16x16x32_bf16 v[66:69], v[214:217], v[198:201], v[66:69]
	s_add_i32 m0, s12, 0xffffff80
	s_barrier
	ds_read_b128 v[148:151], v243 offset:49152
	ds_read_b128 v[152:155], v243 offset:50176
	ds_read_b128 v[178:181], v243 offset:51200
	ds_read_b128 v[182:185], v243 offset:52224
	ds_read_b128 v[186:189], v243 offset:53248
	ds_read_b128 v[190:193], v243 offset:54272
	ds_read_b128 v[194:197], v243 offset:55296
	ds_read_b128 v[198:201], v243 offset:56320
	global_load_lds_dwordx4 v[230:231], off offset:128
	s_add_i32 m0, s28, 0xffffff80
	s_nop 0
	global_load_lds_dwordx4 v[232:233], off offset:128
	s_barrier
	s_waitcnt lgkmcnt(0)
	s_waitcnt lgkmcnt(0)
	v_mfma_f32_16x16x32_bf16 v[62:65], v[132:135], v[148:151], v[62:65]
	v_mfma_f32_16x16x32_bf16 v[58:61], v[140:143], v[148:151], v[58:61]
	v_mfma_f32_16x16x32_bf16 v[46:49], v[132:135], v[178:181], v[46:49]
	v_mfma_f32_16x16x32_bf16 v[42:45], v[140:143], v[178:181], v[42:45]
	v_mfma_f32_16x16x32_bf16 v[34:37], v[132:135], v[186:189], v[34:37]
	v_mfma_f32_16x16x32_bf16 v[26:29], v[140:143], v[186:189], v[26:29]
	v_mfma_f32_16x16x32_bf16 v[18:21], v[132:135], v[194:197], v[18:21]
	v_mfma_f32_16x16x32_bf16 v[10:13], v[140:143], v[194:197], v[10:13]
	v_mfma_f32_16x16x32_bf16 v[62:65], v[136:139], v[152:155], v[62:65]
	v_mfma_f32_16x16x32_bf16 v[58:61], v[144:147], v[152:155], v[58:61]
	v_mfma_f32_16x16x32_bf16 v[46:49], v[136:139], v[182:185], v[46:49]
	v_mfma_f32_16x16x32_bf16 v[42:45], v[144:147], v[182:185], v[42:45]
	v_mfma_f32_16x16x32_bf16 v[34:37], v[136:139], v[190:193], v[34:37]
	v_mfma_f32_16x16x32_bf16 v[26:29], v[144:147], v[190:193], v[26:29]
	v_mfma_f32_16x16x32_bf16 v[18:21], v[136:139], v[198:201], v[18:21]
	v_mfma_f32_16x16x32_bf16 v[10:13], v[144:147], v[198:201], v[10:13]
	s_barrier
	s_add_i32 s4, s5, s3
	s_add_i32 m0, s4, 0xffffff80
	s_nop 0
	global_load_lds_dwordx4 v[244:245], off offset:128
	s_add_i32 m0, s4, 0x1f80
	s_nop 0
	global_load_lds_dwordx4 v[246:247], off offset:128
	s_waitcnt vmcnt(6)
	s_barrier
	v_mfma_f32_16x16x32_bf16 v[54:57], v[202:205], v[148:151], v[54:57]
	v_mfma_f32_16x16x32_bf16 v[50:53], v[210:213], v[148:151], v[50:53]
	v_mfma_f32_16x16x32_bf16 v[38:41], v[202:205], v[178:181], v[38:41]
	v_mfma_f32_16x16x32_bf16 v[30:33], v[210:213], v[178:181], v[30:33]
	v_mfma_f32_16x16x32_bf16 v[22:25], v[202:205], v[186:189], v[22:25]
	v_mfma_f32_16x16x32_bf16 v[14:17], v[210:213], v[186:189], v[14:17]
	v_mfma_f32_16x16x32_bf16 v[6:9], v[202:205], v[194:197], v[6:9]
	v_mfma_f32_16x16x32_bf16 v[2:5], v[210:213], v[194:197], v[2:5]
	v_mfma_f32_16x16x32_bf16 v[54:57], v[206:209], v[152:155], v[54:57]
	v_mfma_f32_16x16x32_bf16 v[50:53], v[214:217], v[152:155], v[50:53]
	v_mfma_f32_16x16x32_bf16 v[38:41], v[206:209], v[182:185], v[38:41]
	v_mfma_f32_16x16x32_bf16 v[30:33], v[214:217], v[182:185], v[30:33]
	v_mfma_f32_16x16x32_bf16 v[22:25], v[206:209], v[190:193], v[22:25]
	v_mfma_f32_16x16x32_bf16 v[14:17], v[214:217], v[190:193], v[14:17]
	v_mfma_f32_16x16x32_bf16 v[6:9], v[206:209], v[198:201], v[6:9]
	v_mfma_f32_16x16x32_bf16 v[2:5], v[214:217], v[198:201], v[2:5]
	s_add_u32 s6, s6, 0x100
	s_addc_u32 s7, s7, 0
	v_lshl_add_u64 v[130:131], v[130:131], 0, s[86:87]
	s_cmp_ge_u32 s42, s13
	s_mov_b32 s4, s42
	s_barrier
	s_cbranch_scc0 .LBB0_649
	s_lshl_b32 s6, s23, 8
	v_lshl_or_b32 v178, s22, 8, v238
	v_add_u32_e32 v130, s6, v1
	v_ashrrev_i32_e32 v179, 31, v178
	v_lshlrev_b64 v[186:187], 1, v[178:179]
	v_ashrrev_i32_e32 v131, 31, v130
	v_lshl_add_u64 v[190:191], s[18:19], 0, v[186:187]
	v_lshlrev_b64 v[188:189], 11, v[130:131]
	v_lshl_add_u64 v[132:133], v[190:191], 0, v[188:189]
	global_load_dwordx4 v[192:195], v[132:133], off
	global_load_dwordx4 v[154:157], v[132:133], off offset:256
	v_or_b32_e32 v132, 16, v130
	v_ashrrev_i32_e32 v133, 31, v132
	v_lshlrev_b64 v[184:185], 11, v[132:133]
	v_lshl_add_u64 v[132:133], v[190:191], 0, v[184:185]
	global_load_dwordx4 v[150:153], v[132:133], off
	global_load_dwordx4 v[146:149], v[132:133], off offset:256
	v_or_b32_e32 v132, 32, v130
	v_ashrrev_i32_e32 v133, 31, v132
	v_lshlrev_b64 v[182:183], 11, v[132:133]
	v_or_b32_e32 v130, 48, v130
	v_lshl_add_u64 v[132:133], v[190:191], 0, v[182:183]
	v_ashrrev_i32_e32 v131, 31, v130
	global_load_dwordx4 v[142:145], v[132:133], off
	global_load_dwordx4 v[138:141], v[132:133], off offset:256
	v_lshlrev_b64 v[180:181], 11, v[130:131]
	v_lshl_add_u64 v[130:131], v[190:191], 0, v[180:181]
	global_load_dwordx4 v[134:137], v[130:131], off
	s_nop 0
	global_load_dwordx4 v[130:133], v[130:131], off offset:256
	v_mov_b32_e32 v169, v168
	s_mov_b64 s[4:5], 0x40000
	v_cmp_lt_i32_e32 vcc, v227, v222
	s_waitcnt vmcnt(0)
	v_lshlrev_b32_e32 v196, 16, v192
	v_and_b32_e32 v197, 0xffff0000, v192
	v_lshlrev_b32_e32 v192, 16, v193
	v_and_b32_e32 v193, 0xffff0000, v193
	v_lshlrev_b32_e32 v198, 16, v194
	v_and_b32_e32 v199, 0xffff0000, v194
	v_lshlrev_b32_e32 v194, 16, v195
	v_and_b32_e32 v195, 0xffff0000, v195
	v_pk_fma_f32 v[128:129], v[168:169], v[128:129], v[192:193]
	v_pk_fma_f32 v[126:127], v[170:171], v[126:127], v[196:197]
	v_pk_fma_f32 v[192:193], v[168:169], v[124:125], v[194:195]
	v_pk_fma_f32 v[124:125], v[170:171], v[122:123], v[198:199]
	v_mul_f32_e32 v122, v127, v127
	v_mul_f32_e32 v123, v129, v129
	v_fmac_f32_e32 v122, v126, v126
	v_fmac_f32_e32 v123, v128, v128
	v_add_f32_e32 v122, v122, v123
	v_mul_f32_e32 v123, v125, v125
	v_mul_f32_e32 v194, v193, v193
	v_fmac_f32_e32 v123, v124, v124
	v_fmac_f32_e32 v194, v192, v192
	v_add_f32_e32 v123, v123, v194
	v_add_f32_e32 v194, v122, v123
	v_cvt_pk_bf16_f32 v122, v126, v127
	v_cvt_pk_bf16_f32 v123, v128, v129
	v_lshlrev_b32_e32 v126, 16, v154
	v_and_b32_e32 v127, 0xffff0000, v154
	v_lshlrev_b32_e32 v128, 16, v155
	v_and_b32_e32 v129, 0xffff0000, v155
	v_lshlrev_b32_e32 v154, 16, v156
	v_and_b32_e32 v155, 0xffff0000, v156
	v_lshlrev_b32_e32 v156, 16, v157
	v_and_b32_e32 v157, 0xffff0000, v157
	v_pk_fma_f32 v[120:121], v[168:169], v[120:121], v[128:129]
	v_pk_fma_f32 v[118:119], v[170:171], v[118:119], v[126:127]
	v_pk_fma_f32 v[126:127], v[168:169], v[116:117], v[156:157]
	v_pk_fma_f32 v[116:117], v[170:171], v[114:115], v[154:155]
	v_mul_f32_e32 v114, v119, v119
	v_mul_f32_e32 v115, v121, v121
	v_fmac_f32_e32 v114, v118, v118
	v_fmac_f32_e32 v115, v120, v120
	v_add_f32_e32 v114, v114, v115
	v_mul_f32_e32 v115, v117, v117
	v_mul_f32_e32 v128, v127, v127
	v_fmac_f32_e32 v115, v116, v116
	v_fmac_f32_e32 v128, v126, v126
	v_add_f32_e32 v115, v115, v128
	v_add_f32_e32 v114, v114, v115
	v_cvt_pk_bf16_f32 v124, v124, v125
	v_cvt_pk_bf16_f32 v125, v192, v193
	v_add_f32_e32 v244, v194, v114
	v_cvt_pk_bf16_f32 v114, v118, v119
	v_cvt_pk_bf16_f32 v115, v120, v121
	v_lshlrev_b32_e32 v118, 16, v150
	v_and_b32_e32 v119, 0xffff0000, v150
	v_lshlrev_b32_e32 v120, 16, v151
	v_and_b32_e32 v121, 0xffff0000, v151
	v_pk_fma_f32 v[154:155], v[168:169], v[112:113], v[120:121]
	v_pk_fma_f32 v[156:157], v[170:171], v[110:111], v[118:119]
	v_lshlrev_b32_e32 v110, 16, v146
	v_and_b32_e32 v111, 0xffff0000, v146
	v_lshlrev_b32_e32 v112, 16, v147
	v_and_b32_e32 v113, 0xffff0000, v147
	v_lshlrev_b32_e32 v118, 16, v148
	v_and_b32_e32 v119, 0xffff0000, v148
	v_lshlrev_b32_e32 v120, 16, v149
	v_and_b32_e32 v121, 0xffff0000, v149
	v_pk_fma_f32 v[146:147], v[168:169], v[104:105], v[112:113]
	v_pk_fma_f32 v[192:193], v[170:171], v[102:103], v[110:111]
	v_pk_fma_f32 v[148:149], v[168:169], v[96:97], v[120:121]
	v_pk_fma_f32 v[198:199], v[170:171], v[94:95], v[118:119]
	v_lshlrev_b32_e32 v94, 16, v142
	v_and_b32_e32 v95, 0xffff0000, v142
	v_lshlrev_b32_e32 v96, 16, v143
	v_and_b32_e32 v97, 0xffff0000, v143
	v_lshlrev_b32_e32 v110, 16, v144
	v_and_b32_e32 v111, 0xffff0000, v144
	v_lshlrev_b32_e32 v112, 16, v145
	v_and_b32_e32 v113, 0xffff0000, v145
	v_pk_fma_f32 v[142:143], v[168:169], v[100:101], v[96:97]
	v_pk_fma_f32 v[194:195], v[170:171], v[98:99], v[94:95]
	v_pk_fma_f32 v[144:145], v[168:169], v[92:93], v[112:113]
	v_pk_fma_f32 v[196:197], v[170:171], v[90:91], v[110:111]
	v_lshlrev_b32_e32 v90, 16, v138
	v_and_b32_e32 v91, 0xffff0000, v138
	v_lshlrev_b32_e32 v92, 16, v139
	v_and_b32_e32 v93, 0xffff0000, v139
	v_lshlrev_b32_e32 v98, 16, v140
	v_and_b32_e32 v99, 0xffff0000, v140
	v_lshlrev_b32_e32 v100, 16, v141
	v_and_b32_e32 v101, 0xffff0000, v141
	v_pk_fma_f32 v[200:201], v[168:169], v[88:89], v[92:93]
	v_pk_fma_f32 v[208:209], v[170:171], v[86:87], v[90:91]
	v_pk_fma_f32 v[204:205], v[168:169], v[80:81], v[100:101]
	v_pk_fma_f32 v[210:211], v[170:171], v[78:79], v[98:99]
	v_lshlrev_b32_e32 v78, 16, v134
	v_and_b32_e32 v79, 0xffff0000, v134
	v_lshlrev_b32_e32 v80, 16, v135
	v_and_b32_e32 v81, 0xffff0000, v135
	v_lshlrev_b32_e32 v86, 16, v136
	v_and_b32_e32 v87, 0xffff0000, v136
	v_lshlrev_b32_e32 v88, 16, v137
	v_and_b32_e32 v89, 0xffff0000, v137
	v_cvt_pk_bf16_f32 v116, v116, v117
	v_cvt_pk_bf16_f32 v117, v126, v127
	v_lshlrev_b32_e32 v126, 16, v152
	v_and_b32_e32 v127, 0xffff0000, v152
	v_lshlrev_b32_e32 v128, 16, v153
	v_and_b32_e32 v129, 0xffff0000, v153
	v_pk_fma_f32 v[138:139], v[168:169], v[84:85], v[80:81]
	v_pk_fma_f32 v[202:203], v[170:171], v[82:83], v[78:79]
	v_pk_fma_f32 v[140:141], v[168:169], v[76:77], v[88:89]
	v_pk_fma_f32 v[206:207], v[170:171], v[74:75], v[86:87]
	v_lshlrev_b32_e32 v74, 16, v130
	v_and_b32_e32 v75, 0xffff0000, v130
	v_lshlrev_b32_e32 v76, 16, v131
	v_and_b32_e32 v77, 0xffff0000, v131
	v_lshlrev_b32_e32 v78, 16, v132
	v_and_b32_e32 v79, 0xffff0000, v132
	v_lshlrev_b32_e32 v80, 16, v133
	v_and_b32_e32 v81, 0xffff0000, v133
	v_lshl_add_u64 v[136:137], v[188:189], 0, s[4:5]
	s_mov_b64 s[4:5], 0x48000
	v_pk_fma_f32 v[150:151], v[168:169], v[108:109], v[128:129]
	v_pk_fma_f32 v[152:153], v[170:171], v[106:107], v[126:127]
	v_cvt_pk_bf16_f32 v106, v156, v157
	v_cvt_pk_bf16_f32 v107, v154, v155
	v_pk_fma_f32 v[212:213], v[168:169], v[72:73], v[76:77]
	v_cvt_pk_bf16_f32 v108, v152, v153
	v_cvt_pk_bf16_f32 v109, v150, v151
	v_cvt_pk_bf16_f32 v102, v192, v193
	v_cvt_pk_bf16_f32 v103, v146, v147
	v_cvt_pk_bf16_f32 v104, v198, v199
	v_cvt_pk_bf16_f32 v105, v148, v149
	v_cvt_pk_bf16_f32 v94, v194, v195
	v_cvt_pk_bf16_f32 v95, v142, v143
	v_cvt_pk_bf16_f32 v96, v196, v197
	v_cvt_pk_bf16_f32 v97, v144, v145
	v_cvt_pk_bf16_f32 v118, v208, v209
	v_cvt_pk_bf16_f32 v119, v200, v201
	v_cvt_pk_bf16_f32 v120, v210, v211
	v_cvt_pk_bf16_f32 v121, v204, v205
	v_cvt_pk_bf16_f32 v98, v202, v203
	v_cvt_pk_bf16_f32 v99, v138, v139
	v_cvt_pk_bf16_f32 v100, v206, v207
	v_cvt_pk_bf16_f32 v101, v140, v141
	v_pk_fma_f32 v[216:217], v[170:171], v[70:71], v[74:75]
	v_pk_fma_f32 v[214:215], v[168:169], v[68:69], v[80:81]
	v_pk_fma_f32 v[218:219], v[170:171], v[66:67], v[78:79]
	v_cvt_pk_bf16_f32 v126, v216, v217
	v_cvt_pk_bf16_f32 v127, v212, v213
	v_lshl_add_u64 v[66:67], v[190:191], 0, v[136:137]
	v_cvt_pk_bf16_f32 v128, v218, v219
	v_cvt_pk_bf16_f32 v129, v214, v215
	v_lshl_add_u64 v[134:135], v[188:189], 0, s[4:5]
	s_mov_b64 s[4:5], 0x50000
	global_load_dwordx4 v[110:113], v[66:67], off
	global_load_dwordx4 v[90:93], v[66:67], off offset:256
	v_lshl_add_u64 v[66:67], v[190:191], 0, v[134:135]
	v_lshl_add_u64 v[132:133], v[188:189], 0, s[4:5]
	s_mov_b64 s[4:5], 0x58000
	global_load_dwordx4 v[86:89], v[66:67], off
	global_load_dwordx4 v[82:85], v[66:67], off offset:256
	v_lshl_add_u64 v[66:67], v[190:191], 0, v[132:133]
	v_lshl_add_u64 v[130:131], v[188:189], 0, s[4:5]
	global_load_dwordx4 v[78:81], v[66:67], off
	global_load_dwordx4 v[74:77], v[66:67], off offset:256
	v_lshl_add_u64 v[66:67], v[190:191], 0, v[130:131]
	global_load_dwordx4 v[70:73], v[66:67], off
	s_nop 0
	global_load_dwordx4 v[66:69], v[66:67], off offset:256
	v_cndmask_b32_e32 v169, v221, v227, vcc
	v_lshl_add_u64 v[188:189], s[18:19], 0, v[188:189]
	v_lshlrev_b32_e32 v190, 2, v169
	v_lshl_add_u64 v[186:187], v[188:189], 0, v[186:187]
	global_store_dwordx4 v[186:187], v[122:125], off
	global_store_dwordx4 v[186:187], v[114:117], off offset:256
	s_nop 1
	v_mov_b32_e32 v114, v244
	s_nop 1
	v_permlane16_swap_b32_e32 v114, v244
	v_cmp_lt_i32_e32 vcc, v228, v222
	s_waitcnt lgkmcnt(0)
	v_add_f32_e32 v114, v244, v114
	v_cndmask_b32_e32 v169, v221, v228, vcc
	v_lshlrev_b32_e32 v191, 2, v169
	v_mov_b32_e32 v115, v114
	s_nop 1
	v_permlane32_swap_b32_e32 v115, v114
	s_and_saveexec_b64 s[4:5], s[38:39]
	s_cbranch_execz .LBB0_652
	s_waitcnt lgkmcnt(0)
	v_add_f32_e32 v114, v114, v115
	v_add_u32_e32 v115, s90, v239
	ds_write_b32 v115, v114
